# lat-A attention: row-max cross-half exchange via v_permlane32_swap and the 0+p first adds of the row-sum chains folded away
# speedup vs baseline: 1.0101x; 1.0033x over previous
.LBB0_225:
	v_sub_f32_e32 v4, v96, v1
	v_exp_f32_e32 v9, v4
	v_sub_f32_e32 v5, v97, v1
	v_exp_f32_e32 v10, v5
	v_sub_f32_e32 v5, v98, v1
	v_exp_f32_e32 v11, v5
	v_sub_f32_e32 v5, v99, v1
	v_exp_f32_e32 v13, v5
	v_sub_f32_e32 v5, v100, v1
	v_exp_f32_e32 v14, v5
	v_sub_f32_e32 v5, v101, v1
	v_add_f32_e32 v4, v10, v9
	v_exp_f32_e32 v15, v5
	v_sub_f32_e32 v5, v102, v1
	v_add_f32_e32 v4, v11, v4
	v_exp_f32_e32 v96, v5
	v_sub_f32_e32 v5, v103, v1
	v_add_f32_e32 v4, v13, v4
	v_exp_f32_e32 v97, v5
	v_sub_f32_e32 v5, v104, v1
	v_add_f32_e32 v4, v14, v4
	v_exp_f32_e32 v5, v5
	v_sub_f32_e32 v6, v105, v1
	v_add_f32_e32 v4, v15, v4
	v_exp_f32_e32 v6, v6
	v_sub_f32_e32 v7, v106, v1
	v_add_f32_e32 v4, v96, v4
	v_exp_f32_e32 v7, v7
	v_sub_f32_e32 v12, v107, v1
	v_add_f32_e32 v4, v97, v4
	v_exp_f32_e32 v12, v12
	v_sub_f32_e32 v98, v108, v1
	v_add_f32_e32 v4, v5, v4
	v_exp_f32_e32 v98, v98
	v_sub_f32_e32 v99, v109, v1
	v_add_f32_e32 v4, v6, v4
	v_exp_f32_e32 v99, v99
	v_sub_f32_e32 v100, v110, v1
	v_add_f32_e32 v4, v7, v4
	v_exp_f32_e32 v100, v100
	v_sub_f32_e32 v101, v111, v1
	v_add_f32_e32 v4, v12, v4
	v_exp_f32_e32 v101, v101
	v_add_f32_e32 v4, v98, v4
	v_add_f32_e32 v4, v99, v4
	v_add_f32_e32 v4, v100, v4
	v_add_f32_e32 v4, v101, v4
	v_add_f32_e32 v3, v3, v4
	v_cvt_pk_bf16_f32 v4, v5, v6
	v_cvt_pk_bf16_f32 v5, v7, v12
	v_cvt_pk_bf16_f32 v12, v9, v10
	v_sub_f32_e32 v9, v80, v159
	v_cvt_pk_bf16_f32 v13, v11, v13
	v_exp_f32_e32 v9, v9
	v_sub_f32_e32 v11, v81, v159
	v_exp_f32_e32 v11, v11
	v_sub_f32_e32 v80, v82, v159
	v_exp_f32_e32 v81, v80
	v_sub_f32_e32 v80, v83, v159
	v_exp_f32_e32 v82, v80
	v_sub_f32_e32 v80, v84, v159
	v_exp_f32_e32 v83, v80
	v_sub_f32_e32 v80, v85, v159
	v_add_f32_e32 v10, v11, v9
	v_exp_f32_e32 v84, v80
	v_sub_f32_e32 v80, v86, v159
	v_add_f32_e32 v10, v81, v10
	v_exp_f32_e32 v85, v80
	v_sub_f32_e32 v80, v87, v159
	v_add_f32_e32 v10, v82, v10
	v_exp_f32_e32 v86, v80
	v_sub_f32_e32 v80, v88, v159
	v_add_f32_e32 v10, v83, v10
	v_exp_f32_e32 v87, v80
	v_sub_f32_e32 v80, v89, v159
	v_add_f32_e32 v10, v84, v10
	v_exp_f32_e32 v88, v80
	v_sub_f32_e32 v80, v90, v159
	v_add_f32_e32 v10, v85, v10
	v_exp_f32_e32 v89, v80
	v_sub_f32_e32 v80, v91, v159
	v_add_f32_e32 v10, v86, v10
	v_exp_f32_e32 v90, v80
	v_sub_f32_e32 v80, v92, v159
	v_add_f32_e32 v10, v87, v10
	v_exp_f32_e32 v91, v80
	v_sub_f32_e32 v80, v93, v159
	v_add_f32_e32 v10, v88, v10
	v_exp_f32_e32 v92, v80
	v_sub_f32_e32 v80, v94, v159
	v_add_f32_e32 v10, v89, v10
	v_exp_f32_e32 v93, v80
	v_sub_f32_e32 v80, v95, v159
	v_add_f32_e32 v10, v90, v10
	v_exp_f32_e32 v94, v80
	v_add_f32_e32 v10, v91, v10
	v_add_f32_e32 v10, v92, v10
	v_add_f32_e32 v10, v93, v10
	v_add_f32_e32 v10, v94, v10
	v_add_f32_e32 v162, v8, v10
	v_cvt_pk_bf16_f32 v81, v81, v82
	v_cvt_pk_bf16_f32 v82, v83, v84
	v_cvt_pk_bf16_f32 v8, v87, v88
	v_lshl_add_u32 v84, v158, 1, v204
	v_lshl_add_u32 v88, v157, 1, v204
	v_cvt_pk_bf16_f32 v80, v9, v11
	v_cvt_pk_bf16_f32 v83, v85, v86
	v_cvt_pk_bf16_f32 v9, v89, v90
	v_cvt_pk_bf16_f32 v10, v91, v92
	ds_read_b64 v[222:223], v84 offset:8192
	ds_read_b64 v[226:227], v84 offset:12288
	ds_read_b64 v[224:225], v88 offset:8192
	ds_read_b64 v[228:229], v88 offset:12288
	v_lshl_add_u32 v246, v156, 1, v204
	v_lshl_add_u32 v247, v155, 1, v204
	ds_read_b64 v[238:239], v246 offset:8192
	ds_read_b64 v[242:243], v246 offset:12288
	ds_read_b64 v[240:241], v247 offset:8192
	ds_read_b64 v[244:245], v247 offset:12288
	v_cvt_pk_bf16_f32 v11, v93, v94
	v_cvt_pk_bf16_f32 v14, v14, v15
	v_cvt_pk_bf16_f32 v15, v96, v97
	s_waitcnt lgkmcnt(0)
	v_mfma_f32_32x32x16_bf16 v[64:79], v[222:225], v[12:15], v[64:79]
	v_cvt_pk_bf16_f32 v6, v98, v99
	v_cvt_pk_bf16_f32 v7, v100, v101
	s_add_i32 s40, s40, 1
	s_add_i32 s2, s41, 1
	s_cmp_lg_u32 s41, 2
	s_cselect_b32 s41, s2, 0
	s_mov_b64 s[2:3], 0x2000
	v_mfma_f32_32x32x16_bf16 v[32:47], v[222:225], v[80:83], v[32:47]
	v_lshl_add_u64 v[150:151], v[150:151], 0, s[22:23]
	v_lshl_add_u64 v[152:153], v[152:153], 0, s[2:3]
	s_cmp_lg_u32 s40, 3
	v_mfma_f32_32x32x16_bf16 v[48:63], v[226:229], v[12:15], v[48:63]
	v_mfma_f32_32x32x16_bf16 v[16:31], v[226:229], v[80:83], v[16:31]
	v_mfma_f32_32x32x16_bf16 v[64:79], v[238:241], v[4:7], v[64:79]
	v_mfma_f32_32x32x16_bf16 v[32:47], v[238:241], v[8:11], v[32:47]
	v_mfma_f32_32x32x16_bf16 v[48:63], v[242:245], v[4:7], v[48:63]
	v_mfma_f32_32x32x16_bf16 v[16:31], v[242:245], v[8:11], v[16:31]
	s_cbranch_scc0 .LBB0_236

.LBB0_232:
	v_sub_f32_e32 v4, v96, v1
	v_exp_f32_e32 v4, v4
	v_sub_f32_e32 v6, v97, v1
	v_exp_f32_e32 v6, v6
	v_sub_f32_e32 v7, v98, v1
	v_exp_f32_e32 v7, v7
	v_sub_f32_e32 v8, v99, v1
	v_exp_f32_e32 v8, v8
	v_add_f32_e32 v5, v6, v4
	v_add_f32_e32 v5, v7, v5
	v_add_f32_e32 v5, v8, v5
	v_cvt_pk_bf16_f32 v97, v7, v8
	v_sub_f32_e32 v8, v80, v159
	v_exp_f32_e32 v207, v8
	v_sub_f32_e32 v8, v81, v159
	v_exp_f32_e32 v209, v8
	v_sub_f32_e32 v8, v82, v159
	v_exp_f32_e32 v210, v8
	v_sub_f32_e32 v8, v83, v159
	v_exp_f32_e32 v211, v8
	v_sub_f32_e32 v8, v84, v159
	v_exp_f32_e32 v212, v8
	v_sub_f32_e32 v8, v85, v159
	v_exp_f32_e32 v213, v8
	v_sub_f32_e32 v8, v86, v159
	v_exp_f32_e32 v214, v8
	v_sub_f32_e32 v8, v87, v159
	v_exp_f32_e32 v215, v8
	v_sub_f32_e32 v8, v88, v159
	v_exp_f32_e32 v216, v8
	v_sub_f32_e32 v8, v89, v159
	v_lshl_add_u32 v204, v154, 1, v204
	v_exp_f32_e32 v217, v8
	v_sub_f32_e32 v8, v90, v159
	v_lshl_add_u32 v84, v164, 1, v204
	v_lshl_add_u32 v88, v163, 1, v204
	v_exp_f32_e32 v218, v8
	v_sub_f32_e32 v8, v91, v159
	ds_read_b64 v[222:223], v84 offset:8192
	ds_read_b64 v[226:227], v84 offset:12288
	ds_read_b64 v[224:225], v88 offset:8192
	ds_read_b64 v[228:229], v88 offset:12288
	v_exp_f32_e32 v219, v8
	v_sub_f32_e32 v8, v92, v159
	v_sub_f32_e32 v9, v100, v1
	v_sub_f32_e32 v96, v103, v1
	v_exp_f32_e32 v220, v8
	v_sub_f32_e32 v8, v93, v159
	v_exp_f32_e32 v9, v9
	v_sub_f32_e32 v10, v101, v1
	v_exp_f32_e32 v99, v96
	v_sub_f32_e32 v96, v104, v1
	v_exp_f32_e32 v205, v8
	v_sub_f32_e32 v8, v94, v159
	v_exp_f32_e32 v10, v10
	v_sub_f32_e32 v11, v102, v1
	v_exp_f32_e32 v100, v96
	v_sub_f32_e32 v96, v105, v1
	v_exp_f32_e32 v206, v8
	v_sub_f32_e32 v8, v95, v159
	s_waitcnt lgkmcnt(0)
	v_exp_f32_e32 v11, v11
	v_exp_f32_e32 v101, v96
	v_sub_f32_e32 v96, v106, v1
	v_exp_f32_e32 v102, v96
	v_sub_f32_e32 v96, v107, v1
	v_add_f32_e32 v5, v9, v5
	v_exp_f32_e32 v103, v96
	v_sub_f32_e32 v96, v108, v1
	v_add_f32_e32 v5, v10, v5
	v_exp_f32_e32 v104, v96
	v_sub_f32_e32 v96, v109, v1
	v_cvt_pk_bf16_f32 v80, v207, v209
	v_cvt_pk_bf16_f32 v81, v210, v211
	v_cvt_pk_bf16_f32 v82, v212, v213
	v_cvt_pk_bf16_f32 v83, v214, v215
	v_add_f32_e32 v5, v11, v5
	v_exp_f32_e32 v105, v96
	v_sub_f32_e32 v96, v110, v1
	v_mfma_f32_32x32x16_bf16 v[32:47], v[222:225], v[80:83], v[32:47]
	v_lshl_add_u32 v84, v160, 1, v204
	v_add_f32_e32 v5, v99, v5
	v_exp_f32_e32 v106, v96
	v_sub_f32_e32 v96, v111, v1
	ds_read_b64 v[232:233], v84 offset:8192
	ds_read_b64 v[236:237], v84 offset:12288
	v_add_f32_e32 v5, v100, v5
	v_exp_f32_e32 v107, v96
	v_mfma_f32_32x32x16_bf16 v[16:31], v[226:229], v[80:83], v[16:31]
	v_lshl_add_u32 v80, v161, 1, v204
	ds_read_b64 v[230:231], v80 offset:8192
	ds_read_b64 v[234:235], v80 offset:12288
	v_cvt_pk_bf16_f32 v96, v4, v6
	v_cvt_pk_bf16_f32 v98, v9, v10
	v_cvt_pk_bf16_f32 v99, v11, v99
	v_add_f32_e32 v5, v101, v5
	v_add_f32_e32 v5, v102, v5
	v_mfma_f32_32x32x16_bf16 v[64:79], v[222:225], v[96:99], v[64:79]
	v_add_f32_e32 v5, v103, v5
	v_add_f32_e32 v5, v104, v5
	v_add_f32_e32 v5, v105, v5
	v_add_f32_e32 v5, v106, v5
	v_add_f32_e32 v5, v107, v5
	v_add_f32_e32 v3, v3, v5
	v_cvt_pk_bf16_f32 v4, v100, v101
	v_mfma_f32_32x32x16_bf16 v[48:63], v[226:229], v[96:99], v[48:63]
	s_waitcnt lgkmcnt(0)
	v_cvt_pk_bf16_f32 v5, v102, v103
	v_cvt_pk_bf16_f32 v6, v104, v105
	v_cvt_pk_bf16_f32 v7, v106, v107
	v_exp_f32_e32 v208, v8
	v_cvt_pk_bf16_f32 v8, v216, v217
	v_mfma_f32_32x32x16_bf16 v[64:79], v[230:233], v[4:7], v[64:79]
	v_cvt_pk_bf16_f32 v9, v218, v219
	v_cvt_pk_bf16_f32 v10, v220, v205
	v_cvt_pk_bf16_f32 v11, v206, v208
	v_mfma_f32_32x32x16_bf16 v[48:63], v[234:237], v[4:7], v[48:63]
	ds_read_b128 v[4:7], v13 offset:4096
	v_mfma_f32_32x32x16_bf16 v[32:47], v[230:233], v[8:11], v[32:47]
	v_mfma_f32_32x32x16_bf16 v[16:31], v[234:237], v[8:11], v[16:31]
	s_waitcnt lgkmcnt(0)
	v_mfma_f32_32x32x16_bf16 v[96:111], v[4:7], v[136:139], 0
	v_mfma_f32_32x32x16_bf16 v[80:95], v[4:7], v[140:143], 0
	ds_read_b128 v[4:7], v14 offset:4096
	s_waitcnt lgkmcnt(0)
	v_mfma_f32_32x32x16_bf16 v[96:111], v[4:7], v[124:127], v[96:111]
	v_mfma_f32_32x32x16_bf16 v[80:95], v[4:7], v[132:135], v[80:95]
	ds_read_b128 v[4:7], v15 offset:4096
	s_waitcnt lgkmcnt(0)
	v_mfma_f32_32x32x16_bf16 v[96:111], v[4:7], v[120:123], v[96:111]
	v_mfma_f32_32x32x16_bf16 v[80:95], v[4:7], v[128:131], v[80:95]
	ds_read_b128 v[4:7], v12 offset:4096
	s_waitcnt lgkmcnt(0)
	v_mfma_f32_32x32x16_bf16 v[96:111], v[4:7], v[112:115], v[96:111]
	v_mfma_f32_32x32x16_bf16 v[80:95], v[4:7], v[116:119], v[80:95]
	s_nop 10
	v_max_f32_e32 v4, v97, v97
	v_max_f32_e32 v5, v96, v96
	v_max_f32_e32 v4, v5, v4
	v_max3_f32 v4, v4, v98, v99
	v_max3_f32 v4, v4, v100, v101
	v_max3_f32 v4, v4, v102, v103
	v_max3_f32 v4, v4, v104, v105
	v_max3_f32 v4, v4, v106, v107
	v_max3_f32 v4, v4, v108, v109
	v_max3_f32 v4, v4, v110, v111
	v_mov_b32_e32 v5, v4
	s_nop 1
	v_permlane32_swap_b32_e32 v5, v4
	s_nop 1
	s_waitcnt lgkmcnt(0)
	v_max_f32_e32 v5, v5, v5
	v_max_f32_e32 v4, v4, v5
	v_add_f32_e32 v5, 0x41000000, v1
	v_cmp_gt_f32_e32 vcc, v4, v5
	s_cbranch_vccz .LBB0_234
	v_max_f32_e32 v4, v4, v4
	v_max_f32_e32 v5, v1, v1
	v_max_f32_e32 v5, v5, v4
	v_sub_f32_e32 v1, v1, v5
	v_exp_f32_e32 v4, v1
	v_mov_b32_e32 v1, v5
	v_mul_f32_e32 v3, v3, v4
	v_pk_mul_f32 v[78:79], v[78:79], v[4:5] op_sel_hi:[1,0]
	v_pk_mul_f32 v[76:77], v[76:77], v[4:5] op_sel_hi:[1,0]
	v_pk_mul_f32 v[74:75], v[74:75], v[4:5] op_sel_hi:[1,0]
	v_pk_mul_f32 v[72:73], v[72:73], v[4:5] op_sel_hi:[1,0]
	v_pk_mul_f32 v[70:71], v[70:71], v[4:5] op_sel_hi:[1,0]
	v_pk_mul_f32 v[68:69], v[68:69], v[4:5] op_sel_hi:[1,0]
	v_pk_mul_f32 v[66:67], v[66:67], v[4:5] op_sel_hi:[1,0]
	v_pk_mul_f32 v[64:65], v[64:65], v[4:5] op_sel_hi:[1,0]
	v_pk_mul_f32 v[62:63], v[62:63], v[4:5] op_sel_hi:[1,0]
	v_pk_mul_f32 v[60:61], v[60:61], v[4:5] op_sel_hi:[1,0]
	v_pk_mul_f32 v[58:59], v[58:59], v[4:5] op_sel_hi:[1,0]
	v_pk_mul_f32 v[56:57], v[56:57], v[4:5] op_sel_hi:[1,0]
	v_pk_mul_f32 v[54:55], v[54:55], v[4:5] op_sel_hi:[1,0]
	v_pk_mul_f32 v[52:53], v[52:53], v[4:5] op_sel_hi:[1,0]
	v_pk_mul_f32 v[50:51], v[50:51], v[4:5] op_sel_hi:[1,0]
	v_pk_mul_f32 v[48:49], v[48:49], v[4:5] op_sel_hi:[1,0]
.LBB0_234:
	v_add_f32_e32 v4, v209, v207
	v_add_f32_e32 v4, v210, v4
	v_max_f32_e32 v5, v81, v81
	v_max_f32_e32 v6, v80, v80
	v_add_f32_e32 v4, v211, v4
	v_max_f32_e32 v5, v6, v5
	v_add_f32_e32 v4, v212, v4
	v_max3_f32 v5, v5, v82, v83
	v_add_f32_e32 v4, v213, v4
	v_max3_f32 v5, v5, v84, v85
	v_add_f32_e32 v4, v214, v4
	v_max3_f32 v5, v5, v86, v87
	v_add_f32_e32 v4, v215, v4
	v_max3_f32 v5, v5, v88, v89
	v_add_f32_e32 v4, v216, v4
	v_max3_f32 v5, v5, v90, v91
	v_add_f32_e32 v4, v217, v4
	v_max3_f32 v5, v5, v92, v93
	v_add_f32_e32 v4, v218, v4
	v_max3_f32 v5, v5, v94, v95
	v_add_f32_e32 v4, v219, v4
	v_mov_b32_e32 v6, v5
	s_nop 1
	v_permlane32_swap_b32_e32 v6, v5
	s_nop 1
	v_add_f32_e32 v4, v220, v4
	v_add_f32_e32 v4, v205, v4
	v_add_f32_e32 v4, v206, v4
	v_add_f32_e32 v4, v208, v4
	v_add_f32_e32 v8, v162, v4
	s_waitcnt lgkmcnt(0)
	v_max_f32_e32 v4, v6, v6
	v_max_f32_e32 v4, v5, v4
	v_add_f32_e32 v5, 0x41000000, v159
	v_cmp_gt_f32_e32 vcc, v4, v5
	s_cbranch_vccz .LBB0_225
	v_max_f32_e32 v4, v4, v4
	v_max_f32_e32 v5, v159, v159
	v_max_f32_e32 v5, v5, v4
	v_sub_f32_e32 v4, v159, v5
	v_exp_f32_e32 v4, v4
	v_mov_b32_e32 v159, v5
	v_mul_f32_e32 v8, v8, v4
	v_pk_mul_f32 v[46:47], v[46:47], v[4:5] op_sel_hi:[1,0]
	v_pk_mul_f32 v[44:45], v[44:45], v[4:5] op_sel_hi:[1,0]
	v_pk_mul_f32 v[42:43], v[42:43], v[4:5] op_sel_hi:[1,0]
	v_pk_mul_f32 v[40:41], v[40:41], v[4:5] op_sel_hi:[1,0]
	v_pk_mul_f32 v[38:39], v[38:39], v[4:5] op_sel_hi:[1,0]
	v_pk_mul_f32 v[36:37], v[36:37], v[4:5] op_sel_hi:[1,0]
	v_pk_mul_f32 v[34:35], v[34:35], v[4:5] op_sel_hi:[1,0]
	v_pk_mul_f32 v[32:33], v[32:33], v[4:5] op_sel_hi:[1,0]
	v_pk_mul_f32 v[30:31], v[30:31], v[4:5] op_sel_hi:[1,0]
	v_pk_mul_f32 v[28:29], v[28:29], v[4:5] op_sel_hi:[1,0]
	v_pk_mul_f32 v[26:27], v[26:27], v[4:5] op_sel_hi:[1,0]
	v_pk_mul_f32 v[24:25], v[24:25], v[4:5] op_sel_hi:[1,0]
	v_pk_mul_f32 v[22:23], v[22:23], v[4:5] op_sel_hi:[1,0]
	v_pk_mul_f32 v[20:21], v[20:21], v[4:5] op_sel_hi:[1,0]
	v_pk_mul_f32 v[18:19], v[18:19], v[4:5] op_sel_hi:[1,0]
	v_pk_mul_f32 v[16:17], v[16:17], v[4:5] op_sel_hi:[1,0]
	s_branch .LBB0_225

.LBB0_240:
	v_sub_f32_e32 v4, v96, v1
	v_exp_f32_e32 v4, v4
	v_sub_f32_e32 v6, v97, v1
	v_exp_f32_e32 v6, v6
	v_sub_f32_e32 v7, v98, v1
	v_exp_f32_e32 v7, v7
	v_sub_f32_e32 v8, v99, v1
	v_exp_f32_e32 v8, v8
	v_sub_f32_e32 v9, v100, v1
	v_exp_f32_e32 v9, v9
	v_sub_f32_e32 v10, v101, v1
	v_add_f32_e32 v5, v6, v4
	v_exp_f32_e32 v10, v10
	v_sub_f32_e32 v11, v102, v1
	v_add_f32_e32 v5, v7, v5
	v_exp_f32_e32 v11, v11
	v_sub_f32_e32 v12, v103, v1
	v_add_f32_e32 v5, v8, v5
	v_exp_f32_e32 v99, v12
	v_sub_f32_e32 v12, v104, v1
	v_add_f32_e32 v5, v9, v5
	v_exp_f32_e32 v100, v12
	v_sub_f32_e32 v12, v105, v1
	v_add_f32_e32 v5, v10, v5
	v_exp_f32_e32 v101, v12
	v_sub_f32_e32 v12, v106, v1
	v_add_f32_e32 v5, v11, v5
	v_exp_f32_e32 v102, v12
	v_sub_f32_e32 v12, v107, v1
	v_add_f32_e32 v5, v99, v5
	v_exp_f32_e32 v103, v12
	v_sub_f32_e32 v12, v108, v1
	v_add_f32_e32 v5, v100, v5
	v_exp_f32_e32 v104, v12
	v_sub_f32_e32 v12, v109, v1
	v_add_f32_e32 v5, v101, v5
	v_exp_f32_e32 v105, v12
	v_sub_f32_e32 v12, v110, v1
	v_add_f32_e32 v5, v102, v5
	v_exp_f32_e32 v106, v12
	v_sub_f32_e32 v12, v111, v1
	v_add_f32_e32 v5, v103, v5
	v_exp_f32_e32 v107, v12
	v_add_f32_e32 v5, v104, v5
	v_add_f32_e32 v5, v105, v5
	v_add_f32_e32 v5, v106, v5
	v_add_f32_e32 v5, v107, v5
	v_add_f32_e32 v12, v3, v5
	v_sub_f32_e32 v3, v80, v159
	v_exp_f32_e32 v151, v3
	v_sub_f32_e32 v3, v81, v159
	v_exp_f32_e32 v153, v3
	v_sub_f32_e32 v3, v82, v159
	v_exp_f32_e32 v166, v3
	v_sub_f32_e32 v3, v83, v159
	v_exp_f32_e32 v167, v3
	v_sub_f32_e32 v3, v84, v159
	v_exp_f32_e32 v201, v3
	v_sub_f32_e32 v3, v85, v159
	v_exp_f32_e32 v202, v3
	v_sub_f32_e32 v3, v86, v159
	v_exp_f32_e32 v203, v3
	v_sub_f32_e32 v3, v87, v159
	v_exp_f32_e32 v204, v3
	v_sub_f32_e32 v3, v88, v159
	v_exp_f32_e32 v205, v3
	v_sub_f32_e32 v3, v89, v159
	v_exp_f32_e32 v206, v3
	v_sub_f32_e32 v3, v90, v159
	v_exp_f32_e32 v207, v3
	v_sub_f32_e32 v3, v91, v159
	v_exp_f32_e32 v208, v3
	v_sub_f32_e32 v3, v92, v159
	v_exp_f32_e32 v209, v3
	v_sub_f32_e32 v3, v93, v159
	v_exp_f32_e32 v149, v3
	v_sub_f32_e32 v3, v94, v159
	v_exp_f32_e32 v150, v3
	v_sub_f32_e32 v3, v95, v159
	v_exp_f32_e32 v152, v3
	v_lshl_add_u32 v3, v154, 1, v165
	v_lshl_add_u32 v84, v164, 1, v3
	v_lshl_add_u32 v88, v163, 1, v3
	ds_read_b64 v[222:223], v84 offset:8192
	ds_read_b64 v[226:227], v84 offset:12288
	ds_read_b64 v[224:225], v88 offset:8192
	ds_read_b64 v[228:229], v88 offset:12288
	v_cvt_pk_bf16_f32 v80, v151, v153
	v_cvt_pk_bf16_f32 v81, v166, v167
	v_cvt_pk_bf16_f32 v82, v201, v202
	s_waitcnt lgkmcnt(0)
	v_cvt_pk_bf16_f32 v83, v203, v204
	v_lshl_add_u32 v84, v160, 1, v3
	ds_read_b64 v[232:233], v84 offset:8192
	ds_read_b64 v[236:237], v84 offset:12288
	v_mfma_f32_32x32x16_bf16 v[32:47], v[222:225], v[80:83], v[32:47]
	v_cvt_pk_bf16_f32 v96, v4, v6
	v_cvt_pk_bf16_f32 v97, v7, v8
	v_cvt_pk_bf16_f32 v98, v9, v10
	v_cvt_pk_bf16_f32 v99, v11, v99
	v_cvt_pk_bf16_f32 v4, v100, v101
	v_cvt_pk_bf16_f32 v5, v102, v103
	v_cvt_pk_bf16_f32 v6, v104, v105
	v_mfma_f32_32x32x16_bf16 v[16:31], v[226:229], v[80:83], v[16:31]
	v_lshl_add_u32 v80, v161, 1, v3
	ds_read_b64 v[230:231], v80 offset:8192
	ds_read_b64 v[234:235], v80 offset:12288
	v_cvt_pk_bf16_f32 v7, v106, v107
	v_cvt_pk_bf16_f32 v8, v205, v206
	v_cvt_pk_bf16_f32 v9, v207, v208
	v_cvt_pk_bf16_f32 v10, v209, v149
	v_cvt_pk_bf16_f32 v11, v150, v152
	v_mfma_f32_32x32x16_bf16 v[64:79], v[222:225], v[96:99], v[64:79]
	v_mfma_f32_32x32x16_bf16 v[48:63], v[226:229], v[96:99], v[48:63]
	s_waitcnt lgkmcnt(0)
	v_mfma_f32_32x32x16_bf16 v[64:79], v[230:233], v[4:7], v[64:79]
	s_nop 0
	v_mfma_f32_32x32x16_bf16 v[48:63], v[234:237], v[4:7], v[48:63]
	ds_read_b128 v[4:7], v14 offset:4096
	v_mfma_f32_32x32x16_bf16 v[32:47], v[230:233], v[8:11], v[32:47]
	v_mfma_f32_32x32x16_bf16 v[16:31], v[234:237], v[8:11], v[16:31]
	s_waitcnt lgkmcnt(0)
	v_mfma_f32_32x32x16_bf16 v[96:111], v[4:7], v[136:139], 0
	v_mfma_f32_32x32x16_bf16 v[80:95], v[4:7], v[140:143], 0
	ds_read_b128 v[4:7], v15 offset:4096
	s_waitcnt lgkmcnt(0)
	v_mfma_f32_32x32x16_bf16 v[96:111], v[4:7], v[124:127], v[96:111]
	v_mfma_f32_32x32x16_bf16 v[80:95], v[4:7], v[132:135], v[80:95]
	ds_read_b128 v[4:7], v148 offset:4096
	s_waitcnt lgkmcnt(0)
	v_mfma_f32_32x32x16_bf16 v[96:111], v[4:7], v[120:123], v[96:111]
	v_mfma_f32_32x32x16_bf16 v[80:95], v[4:7], v[128:131], v[80:95]
	ds_read_b128 v[4:7], v13 offset:4096
	s_waitcnt lgkmcnt(0)
	v_mfma_f32_32x32x16_bf16 v[96:111], v[4:7], v[112:115], v[96:111]
	v_mfma_f32_32x32x16_bf16 v[80:95], v[4:7], v[116:119], v[80:95]
	s_nop 10
	v_max_f32_e32 v4, v97, v97
	v_max_f32_e32 v5, v96, v96
	v_max_f32_e32 v4, v5, v4
	v_max3_f32 v4, v4, v98, v99
	v_max3_f32 v4, v4, v100, v101
	v_max3_f32 v4, v4, v102, v103
	v_max3_f32 v4, v4, v104, v105
	v_max3_f32 v4, v4, v106, v107
	v_max3_f32 v4, v4, v108, v109
	v_max3_f32 v4, v4, v110, v111
	v_mov_b32_e32 v5, v4
	s_nop 1
	v_permlane32_swap_b32_e32 v5, v4
	s_nop 1
	s_waitcnt lgkmcnt(0)
	v_max_f32_e32 v5, v5, v5
	v_max_f32_e32 v4, v4, v5
	v_add_f32_e32 v5, 0x41000000, v1
	v_cmp_gt_f32_e32 vcc, v4, v5
	s_cbranch_vccz .LBB0_242
	v_max_f32_e32 v4, v4, v4
	v_max_f32_e32 v5, v1, v1
	v_max_f32_e32 v5, v5, v4
	v_sub_f32_e32 v1, v1, v5
	v_exp_f32_e32 v4, v1
	v_mov_b32_e32 v1, v5
	v_mul_f32_e32 v12, v12, v4
	v_pk_mul_f32 v[78:79], v[78:79], v[4:5] op_sel_hi:[1,0]
	v_pk_mul_f32 v[76:77], v[76:77], v[4:5] op_sel_hi:[1,0]
	v_pk_mul_f32 v[74:75], v[74:75], v[4:5] op_sel_hi:[1,0]
	v_pk_mul_f32 v[72:73], v[72:73], v[4:5] op_sel_hi:[1,0]
	v_pk_mul_f32 v[70:71], v[70:71], v[4:5] op_sel_hi:[1,0]
	v_pk_mul_f32 v[68:69], v[68:69], v[4:5] op_sel_hi:[1,0]
	v_pk_mul_f32 v[66:67], v[66:67], v[4:5] op_sel_hi:[1,0]
	v_pk_mul_f32 v[64:65], v[64:65], v[4:5] op_sel_hi:[1,0]
	v_pk_mul_f32 v[62:63], v[62:63], v[4:5] op_sel_hi:[1,0]
	v_pk_mul_f32 v[60:61], v[60:61], v[4:5] op_sel_hi:[1,0]
	v_pk_mul_f32 v[58:59], v[58:59], v[4:5] op_sel_hi:[1,0]
	v_pk_mul_f32 v[56:57], v[56:57], v[4:5] op_sel_hi:[1,0]
	v_pk_mul_f32 v[54:55], v[54:55], v[4:5] op_sel_hi:[1,0]
	v_pk_mul_f32 v[52:53], v[52:53], v[4:5] op_sel_hi:[1,0]
	v_pk_mul_f32 v[50:51], v[50:51], v[4:5] op_sel_hi:[1,0]
	v_pk_mul_f32 v[48:49], v[48:49], v[4:5] op_sel_hi:[1,0]
.LBB0_242:
	v_add_f32_e32 v4, v153, v151
	v_add_f32_e32 v4, v166, v4
	v_max_f32_e32 v5, v81, v81
	v_max_f32_e32 v6, v80, v80
	v_add_f32_e32 v4, v167, v4
	v_max_f32_e32 v5, v6, v5
	v_add_f32_e32 v4, v201, v4
	v_max3_f32 v5, v5, v82, v83
	v_add_f32_e32 v4, v202, v4
	v_max3_f32 v5, v5, v84, v85
	v_add_f32_e32 v4, v203, v4
	v_max3_f32 v5, v5, v86, v87
	v_add_f32_e32 v4, v204, v4
	v_max3_f32 v5, v5, v88, v89
	v_add_f32_e32 v4, v205, v4
	v_max3_f32 v5, v5, v90, v91
	v_add_f32_e32 v4, v206, v4
	v_max3_f32 v5, v5, v92, v93
	v_add_f32_e32 v4, v207, v4
	v_max3_f32 v5, v5, v94, v95
	v_add_f32_e32 v4, v208, v4
	v_mov_b32_e32 v6, v5
	s_nop 1
	v_permlane32_swap_b32_e32 v6, v5
	s_nop 1
	v_add_f32_e32 v4, v209, v4
	v_add_f32_e32 v4, v149, v4
	v_add_f32_e32 v4, v150, v4
	v_add_f32_e32 v4, v152, v4
	v_add_f32_e32 v8, v162, v4
	s_waitcnt lgkmcnt(0)
	v_max_f32_e32 v4, v6, v6
	v_max_f32_e32 v4, v5, v4
	v_add_f32_e32 v5, 0x41000000, v159
	v_cmp_gt_f32_e32 vcc, v4, v5
	s_cbranch_vccz .LBB0_244
	v_max_f32_e32 v4, v4, v4
	v_max_f32_e32 v5, v159, v159
	v_max_f32_e32 v5, v5, v4
	v_sub_f32_e32 v4, v159, v5
	v_exp_f32_e32 v4, v4
	v_mov_b32_e32 v159, v5
	v_mul_f32_e32 v8, v8, v4
	v_pk_mul_f32 v[46:47], v[46:47], v[4:5] op_sel_hi:[1,0]
	v_pk_mul_f32 v[44:45], v[44:45], v[4:5] op_sel_hi:[1,0]
	v_pk_mul_f32 v[42:43], v[42:43], v[4:5] op_sel_hi:[1,0]
	v_pk_mul_f32 v[40:41], v[40:41], v[4:5] op_sel_hi:[1,0]
	v_pk_mul_f32 v[38:39], v[38:39], v[4:5] op_sel_hi:[1,0]
	v_pk_mul_f32 v[36:37], v[36:37], v[4:5] op_sel_hi:[1,0]
	v_pk_mul_f32 v[34:35], v[34:35], v[4:5] op_sel_hi:[1,0]
	v_pk_mul_f32 v[32:33], v[32:33], v[4:5] op_sel_hi:[1,0]
	v_pk_mul_f32 v[30:31], v[30:31], v[4:5] op_sel_hi:[1,0]
	v_pk_mul_f32 v[28:29], v[28:29], v[4:5] op_sel_hi:[1,0]
	v_pk_mul_f32 v[26:27], v[26:27], v[4:5] op_sel_hi:[1,0]
	v_pk_mul_f32 v[24:25], v[24:25], v[4:5] op_sel_hi:[1,0]
	v_pk_mul_f32 v[22:23], v[22:23], v[4:5] op_sel_hi:[1,0]
	v_pk_mul_f32 v[20:21], v[20:21], v[4:5] op_sel_hi:[1,0]
	v_pk_mul_f32 v[18:19], v[18:19], v[4:5] op_sel_hi:[1,0]
	v_pk_mul_f32 v[16:17], v[16:17], v[4:5] op_sel_hi:[1,0]
.LBB0_244:
	v_sub_f32_e32 v4, v96, v1
	v_exp_f32_e32 v9, v4
	v_sub_f32_e32 v5, v97, v1
	v_exp_f32_e32 v10, v5
	v_sub_f32_e32 v5, v98, v1
	v_exp_f32_e32 v11, v5
	v_sub_f32_e32 v5, v99, v1
	v_exp_f32_e32 v13, v5
	v_sub_f32_e32 v5, v100, v1
	v_exp_f32_e32 v14, v5
	v_sub_f32_e32 v5, v101, v1
	v_add_f32_e32 v4, v10, v9
	v_exp_f32_e32 v15, v5
	v_sub_f32_e32 v5, v102, v1
	v_add_f32_e32 v4, v11, v4
	v_exp_f32_e32 v96, v5
	v_sub_f32_e32 v5, v103, v1
	v_add_f32_e32 v4, v13, v4
	v_exp_f32_e32 v97, v5
	v_sub_f32_e32 v5, v104, v1
	v_add_f32_e32 v4, v14, v4
	v_exp_f32_e32 v5, v5
	v_sub_f32_e32 v6, v105, v1
	v_add_f32_e32 v4, v15, v4
	v_exp_f32_e32 v6, v6
	v_sub_f32_e32 v7, v106, v1
	v_add_f32_e32 v4, v96, v4
	v_exp_f32_e32 v7, v7
	v_sub_f32_e32 v98, v107, v1
	v_add_f32_e32 v4, v97, v4
	v_exp_f32_e32 v98, v98
	v_sub_f32_e32 v99, v108, v1
	v_add_f32_e32 v4, v5, v4
	v_exp_f32_e32 v99, v99
	v_sub_f32_e32 v100, v109, v1
	v_add_f32_e32 v4, v6, v4
	v_exp_f32_e32 v100, v100
	v_sub_f32_e32 v101, v110, v1
	v_add_f32_e32 v4, v7, v4
	v_exp_f32_e32 v101, v101
	v_sub_f32_e32 v1, v111, v1
	v_add_f32_e32 v4, v98, v4
	v_exp_f32_e32 v1, v1
	v_add_f32_e32 v4, v99, v4
	v_add_f32_e32 v4, v100, v4
	v_add_f32_e32 v4, v101, v4
	v_add_f32_e32 v4, v1, v4
	v_add_f32_e32 v102, v12, v4
	v_cvt_pk_bf16_f32 v4, v5, v6
	v_cvt_pk_bf16_f32 v5, v7, v98
	v_cvt_pk_bf16_f32 v7, v101, v1
	v_sub_f32_e32 v1, v80, v159
	v_cvt_pk_bf16_f32 v12, v9, v10
	v_exp_f32_e32 v1, v1
	v_sub_f32_e32 v10, v81, v159
	v_cvt_pk_bf16_f32 v13, v11, v13
	v_exp_f32_e32 v10, v10
	v_sub_f32_e32 v11, v82, v159
	v_exp_f32_e32 v11, v11
	v_sub_f32_e32 v80, v83, v159
	v_exp_f32_e32 v81, v80
	v_sub_f32_e32 v80, v84, v159
	v_exp_f32_e32 v82, v80
	v_sub_f32_e32 v80, v85, v159
	v_add_f32_e32 v9, v10, v1
	v_exp_f32_e32 v83, v80
	v_sub_f32_e32 v80, v86, v159
	v_add_f32_e32 v9, v11, v9
	v_exp_f32_e32 v84, v80
	v_sub_f32_e32 v80, v87, v159
	v_add_f32_e32 v9, v81, v9
	v_exp_f32_e32 v85, v80
	v_sub_f32_e32 v80, v88, v159
	v_add_f32_e32 v9, v82, v9
	v_exp_f32_e32 v86, v80
	v_sub_f32_e32 v80, v89, v159
	v_add_f32_e32 v9, v83, v9
	v_exp_f32_e32 v87, v80
	v_sub_f32_e32 v80, v90, v159
	v_add_f32_e32 v9, v84, v9
	v_exp_f32_e32 v88, v80
	v_sub_f32_e32 v80, v91, v159
	v_add_f32_e32 v9, v85, v9
	v_exp_f32_e32 v89, v80
	v_sub_f32_e32 v80, v92, v159
	v_add_f32_e32 v9, v86, v9
	v_exp_f32_e32 v90, v80
	v_sub_f32_e32 v80, v93, v159
	v_add_f32_e32 v9, v87, v9
	v_exp_f32_e32 v91, v80
	v_sub_f32_e32 v80, v94, v159
	v_add_f32_e32 v9, v88, v9
	v_exp_f32_e32 v92, v80
	v_sub_f32_e32 v80, v95, v159
	v_add_f32_e32 v9, v89, v9
	v_exp_f32_e32 v93, v80
	v_add_f32_e32 v9, v90, v9
	v_add_f32_e32 v9, v91, v9
	v_add_f32_e32 v9, v92, v9
	v_add_f32_e32 v9, v93, v9
	v_cvt_pk_bf16_f32 v80, v1, v10
	v_lshl_add_u32 v1, v158, 1, v3
	v_cvt_pk_bf16_f32 v14, v14, v15
	v_cvt_pk_bf16_f32 v15, v96, v97
	v_add_f32_e32 v96, v8, v9
	v_cvt_pk_bf16_f32 v82, v82, v83
	v_cvt_pk_bf16_f32 v83, v84, v85
	v_cvt_pk_bf16_f32 v8, v86, v87
	ds_read2st64_b64 v[84:87], v1 offset0:16 offset1:24
	v_lshl_add_u32 v1, v157, 1, v3
	v_cvt_pk_bf16_f32 v9, v88, v89
	v_cvt_pk_bf16_f32 v10, v90, v91
	ds_read2st64_b64 v[88:91], v1 offset0:16 offset1:24
	v_cvt_pk_bf16_f32 v81, v11, v81
	v_cvt_pk_bf16_f32 v11, v92, v93
	s_waitcnt lgkmcnt(0)
	v_mov_b32_e32 v92, v84
	v_mov_b32_e32 v93, v85
	v_mov_b32_e32 v94, v88
	v_mov_b32_e32 v95, v89
	v_mov_b32_e32 v88, v86
	v_mov_b32_e32 v89, v87
	v_lshl_add_u32 v1, v156, 1, v3
	v_mfma_f32_32x32x16_bf16 v[64:79], v[92:95], v[12:15], v[64:79]
	v_cvt_pk_bf16_f32 v6, v99, v100
	v_readlane_b32 s2, v252, 51
	v_readlane_b32 s3, v252, 52
	s_add_u32 s38, s2, s38
	s_addc_u32 s39, s3, s39
	s_add_u32 s2, s38, s36
	s_addc_u32 s3, s39, s37
	v_mfma_f32_32x32x16_bf16 v[48:63], v[88:91], v[12:15], v[48:63]
	ds_read2st64_b64 v[12:15], v1 offset0:16 offset1:24
	v_lshl_add_u32 v1, v155, 1, v3
	s_waitcnt lgkmcnt(0)
	v_mov_b32_e32 v84, v12
	v_mov_b32_e32 v85, v13
	v_mfma_f32_32x32x16_bf16 v[32:47], v[92:95], v[80:83], v[32:47]
	v_mfma_f32_32x32x16_bf16 v[16:31], v[88:91], v[80:83], v[16:31]
	ds_read2st64_b64 v[80:83], v1 offset0:16 offset1:24
	ds_bpermute_b32 v1, v0, v102
	ds_bpermute_b32 v0, v0, v96
	s_waitcnt lgkmcnt(0)
	v_mov_b32_e32 v86, v80
	v_mov_b32_e32 v87, v81
	v_mov_b32_e32 v80, v14
	v_mov_b32_e32 v81, v15
	v_mfma_f32_32x32x16_bf16 v[64:79], v[84:87], v[4:7], v[64:79]
	v_add_f32_e32 v1, v102, v1
	v_add_f32_e32 v0, v96, v0
	v_rcp_f32_e32 v0, v0
	v_mfma_f32_32x32x16_bf16 v[48:63], v[80:83], v[4:7], v[48:63]
	v_rcp_f32_e32 v6, v1
	v_lshlrev_b32_e32 v4, 1, v154
	v_mov_b32_e32 v5, v2
	v_lshl_add_u64 v[4:5], s[2:3], 0, v[4:5]
	s_nop 3
	v_pk_mul_f32 v[12:13], v[66:67], v[6:7] op_sel_hi:[1,0]
	v_mfma_f32_32x32x16_bf16 v[32:47], v[84:87], v[8:11], v[32:47]
	v_mfma_f32_32x32x16_bf16 v[16:31], v[80:83], v[8:11], v[16:31]
	v_mul_f32_e64 v10, v64, v6
	v_mul_f32_e64 v11, v65, v6
	v_lshl_add_u64 v[8:9], v[4:5], 0, v[146:147]
	v_cvt_pk_bf16_f32 v10, v10, v11
	v_cvt_pk_bf16_f32 v11, v12, v13
	global_store_dwordx2 v[8:9], v[10:11], off
	v_pk_mul_f32 v[10:11], v[68:69], v[6:7] op_sel_hi:[1,0]
	v_pk_mul_f32 v[12:13], v[70:71], v[6:7] op_sel_hi:[1,0]
	v_cvt_pk_bf16_f32 v10, v10, v11
	v_cvt_pk_bf16_f32 v11, v12, v13
	global_store_dwordx2 v[8:9], v[10:11], off offset:16
	v_pk_mul_f32 v[10:11], v[72:73], v[6:7] op_sel_hi:[1,0]
	v_pk_mul_f32 v[12:13], v[74:75], v[6:7] op_sel_hi:[1,0]
	v_cvt_pk_bf16_f32 v10, v10, v11
	v_cvt_pk_bf16_f32 v11, v12, v13
	global_store_dwordx2 v[8:9], v[10:11], off offset:32
	v_pk_mul_f32 v[10:11], v[76:77], v[6:7] op_sel_hi:[1,0]
	v_pk_mul_f32 v[12:13], v[78:79], v[6:7] op_sel_hi:[1,0]
	v_cvt_pk_bf16_f32 v10, v10, v11
	v_cvt_pk_bf16_f32 v11, v12, v13
	global_store_dwordx2 v[8:9], v[10:11], off offset:48
	v_pk_mul_f32 v[10:11], v[48:49], v[6:7] op_sel_hi:[1,0]
	v_pk_mul_f32 v[12:13], v[50:51], v[6:7] op_sel_hi:[1,0]
	v_cvt_pk_bf16_f32 v10, v10, v11
	v_cvt_pk_bf16_f32 v11, v12, v13
	global_store_dwordx2 v[8:9], v[10:11], off offset:64
	v_pk_mul_f32 v[10:11], v[52:53], v[6:7] op_sel_hi:[1,0]
	v_pk_mul_f32 v[12:13], v[54:55], v[6:7] op_sel_hi:[1,0]
	v_cvt_pk_bf16_f32 v10, v10, v11
	v_cvt_pk_bf16_f32 v11, v12, v13
	global_store_dwordx2 v[8:9], v[10:11], off offset:80
	v_pk_mul_f32 v[10:11], v[56:57], v[6:7] op_sel_hi:[1,0]
	v_pk_mul_f32 v[12:13], v[58:59], v[6:7] op_sel_hi:[1,0]
	v_cvt_pk_bf16_f32 v10, v10, v11
	v_cvt_pk_bf16_f32 v11, v12, v13
	global_store_dwordx2 v[8:9], v[10:11], off offset:96
	v_pk_mul_f32 v[10:11], v[60:61], v[6:7] op_sel_hi:[1,0]
	v_pk_mul_f32 v[6:7], v[62:63], v[6:7] op_sel_hi:[1,0]
	v_cvt_pk_bf16_f32 v10, v10, v11
	v_cvt_pk_bf16_f32 v11, v6, v7
	global_store_dwordx2 v[8:9], v[10:11], off offset:112
	v_pk_mul_f32 v[6:7], v[32:33], v[0:1] op_sel_hi:[1,0]
	v_pk_mul_f32 v[8:9], v[34:35], v[0:1] op_sel_hi:[1,0]
	v_lshl_add_u64 v[4:5], v[4:5], 0, v[144:145]
	v_cvt_pk_bf16_f32 v6, v6, v7
	v_cvt_pk_bf16_f32 v7, v8, v9
	global_store_dwordx2 v[4:5], v[6:7], off
	v_pk_mul_f32 v[6:7], v[36:37], v[0:1] op_sel_hi:[1,0]
	v_pk_mul_f32 v[8:9], v[38:39], v[0:1] op_sel_hi:[1,0]
	v_cvt_pk_bf16_f32 v6, v6, v7
	v_cvt_pk_bf16_f32 v7, v8, v9
	global_store_dwordx2 v[4:5], v[6:7], off offset:16
	v_pk_mul_f32 v[6:7], v[40:41], v[0:1] op_sel_hi:[1,0]
	v_pk_mul_f32 v[8:9], v[42:43], v[0:1] op_sel_hi:[1,0]
	v_cvt_pk_bf16_f32 v6, v6, v7
	v_cvt_pk_bf16_f32 v7, v8, v9
	global_store_dwordx2 v[4:5], v[6:7], off offset:32
	v_pk_mul_f32 v[6:7], v[44:45], v[0:1] op_sel_hi:[1,0]
	v_pk_mul_f32 v[8:9], v[46:47], v[0:1] op_sel_hi:[1,0]
	v_cvt_pk_bf16_f32 v6, v6, v7
	v_cvt_pk_bf16_f32 v7, v8, v9
	global_store_dwordx2 v[4:5], v[6:7], off offset:48
	v_pk_mul_f32 v[6:7], v[16:17], v[0:1] op_sel_hi:[1,0]
	v_pk_mul_f32 v[8:9], v[18:19], v[0:1] op_sel_hi:[1,0]
	v_cvt_pk_bf16_f32 v6, v6, v7
	v_cvt_pk_bf16_f32 v7, v8, v9
	global_store_dwordx2 v[4:5], v[6:7], off offset:64
	v_pk_mul_f32 v[6:7], v[20:21], v[0:1] op_sel_hi:[1,0]
	v_pk_mul_f32 v[8:9], v[22:23], v[0:1] op_sel_hi:[1,0]
	v_cvt_pk_bf16_f32 v6, v6, v7
	v_cvt_pk_bf16_f32 v7, v8, v9
	global_store_dwordx2 v[4:5], v[6:7], off offset:80
	v_pk_mul_f32 v[6:7], v[24:25], v[0:1] op_sel_hi:[1,0]
	v_pk_mul_f32 v[8:9], v[26:27], v[0:1] op_sel_hi:[1,0]
	v_cvt_pk_bf16_f32 v6, v6, v7
	v_cvt_pk_bf16_f32 v7, v8, v9
	global_store_dwordx2 v[4:5], v[6:7], off offset:96
	v_pk_mul_f32 v[6:7], v[28:29], v[0:1] op_sel_hi:[1,0]
	v_pk_mul_f32 v[0:1], v[30:31], v[0:1] op_sel_hi:[1,0]
	v_cvt_pk_bf16_f32 v6, v6, v7
	v_cvt_pk_bf16_f32 v7, v0, v1
	global_store_dwordx2 v[4:5], v[6:7], off offset:112
	s_waitcnt lgkmcnt(0)
	s_waitcnt vmcnt(0)
	s_barrier
